# on top of v29: forgetting-attention pipelined step head issues the LDS reads in first-use order (K fragment 0 + its accumulator image first) with counted lgkmcnt waits before each of the eight QK MFMA
# baseline (speedup 1.0000x reference)
.LBB0_887:
	s_andn2_b64 vcc, exec, s[4:5]
	s_cbranch_vccnz .LBB0_889
	v_add_u32_e32 v246, s33, v202
	v_add_u32_e32 v246, 0x18a00, v246
	s_nop 6
	v_add_u32_e32 v247, s58, v195
	ds_read_b128 v[66:69], v247
	ds_read_b128 v[34:37], v246 offset:256
	ds_read_b128 v[38:41], v246 offset:288
	ds_read_b128 v[42:45], v246 offset:320
	ds_read_b128 v[46:49], v246 offset:352
	ds_read_b128 v[70:73], v247 offset:4096
	ds_read_b128 v[50:53], v246 offset:384
	ds_read_b128 v[54:57], v246 offset:416
	ds_read_b128 v[58:61], v246 offset:448
	ds_read_b128 v[62:65], v246 offset:480
	v_add_u32_e32 v248, s58, v198
	ds_read_b128 v[74:77], v248
	ds_read_b128 v[78:81], v248 offset:4096
	v_add_u32_e32 v249, s58, v199
	ds_read_b128 v[82:85], v249
	ds_read_b128 v[86:89], v249 offset:4096
	v_add_u32_e32 v250, s58, v200
	ds_read_b128 v[90:93], v250
	ds_read_b128 v[94:97], v250 offset:4096
	v_add_u32_e32 v0, s58, v197
	s_waitcnt lgkmcnt(11)
	v_mfma_f32_32x32x16_bf16 v[34:49], v[66:69], v[146:149], v[34:49]
	s_waitcnt lgkmcnt(6)
	v_mfma_f32_32x32x16_bf16 v[50:65], v[70:73], v[146:149], v[50:65]
	s_waitcnt lgkmcnt(5)
	v_mfma_f32_32x32x16_bf16 v[34:49], v[74:77], v[150:153], v[34:49]
	s_waitcnt lgkmcnt(4)
	v_mfma_f32_32x32x16_bf16 v[50:65], v[78:81], v[150:153], v[50:65]
	s_waitcnt lgkmcnt(3)
	v_mfma_f32_32x32x16_bf16 v[34:49], v[82:85], v[154:157], v[34:49]
	s_waitcnt lgkmcnt(2)
	v_mfma_f32_32x32x16_bf16 v[50:65], v[86:89], v[154:157], v[50:65]
	s_waitcnt lgkmcnt(1)
	v_mfma_f32_32x32x16_bf16 v[34:49], v[90:93], v[158:161], v[34:49]
	s_waitcnt lgkmcnt(0)
	v_mfma_f32_32x32x16_bf16 v[50:65], v[94:97], v[158:161], v[50:65]
	s_add_i32 s4, s58, 0x2000
	ds_read_b128 v[82:85], v247 offset:8192
	ds_read_b128 v[66:69], v246
	ds_read_b128 v[70:73], v246 offset:32
	ds_read_b128 v[74:77], v246 offset:64
	ds_read_b128 v[78:81], v246 offset:96
	s_nop 5
	v_exp_f32_e32 v162, v50
	v_exp_f32_e32 v138, v51
	v_exp_f32_e32 v130, v52
	s_waitcnt lgkmcnt(0)
	v_mfma_f32_32x32x16_bf16 v[66:81], v[82:85], v[146:149], v[66:81]
	ds_read_b128 v[82:85], v248 offset:8192
	ds_read_b128 v[86:89], v250 offset:8192
	v_exp_f32_e32 v122, v34
	v_exp_f32_e32 v134, v35
	v_exp_f32_e32 v126, v36
	v_exp_f32_e32 v116, v37
	s_waitcnt lgkmcnt(1)
	v_mfma_f32_32x32x16_bf16 v[66:81], v[82:85], v[150:153], v[66:81]
	ds_read_b128 v[82:85], v249 offset:8192
	ds_read_b128 v[34:37], v247 offset:12288
	ds_read_b128 v[90:93], v246 offset:192
	ds_read_b128 v[94:97], v246 offset:224
	v_exp_f32_e32 v172, v53
	v_exp_f32_e32 v186, v38
	v_exp_f32_e32 v168, v39
	s_waitcnt lgkmcnt(3)
	v_mfma_f32_32x32x16_bf16 v[66:81], v[82:85], v[154:157], v[66:81]
	ds_read_b128 v[82:85], v246 offset:128
	v_exp_f32_e32 v164, v40
	v_exp_f32_e32 v142, v41
	ds_read_b128 v[38:41], v250 offset:12288
	v_exp_f32_e32 v244, v54
	v_exp_f32_e32 v170, v55
	v_exp_f32_e32 v166, v56
	v_mfma_f32_32x32x16_bf16 v[66:81], v[86:89], v[158:161], v[66:81]
	ds_read_b128 v[86:89], v246 offset:160
	ds_read_b128 v[50:53], v248 offset:12288
	v_exp_f32_e32 v144, v57
	v_exp_f32_e32 v136, v42
	v_exp_f32_e32 v140, v58
	v_exp_f32_e32 v128, v43
	v_exp_f32_e32 v132, v59
	s_waitcnt lgkmcnt(1)
	v_mfma_f32_32x32x16_bf16 v[82:97], v[34:37], v[146:149], v[82:97]
	ds_read_b128 v[34:37], v249 offset:12288
	v_exp_f32_e32 v120, v44
	v_exp_f32_e32 v124, v60
	v_exp_f32_e32 v114, v45
	v_exp_f32_e32 v118, v61
	v_exp_f32_e32 v110, v46
	v_exp_f32_e32 v112, v62
	s_waitcnt lgkmcnt(1)
	v_mfma_f32_32x32x16_bf16 v[82:97], v[50:53], v[150:153], v[82:97]
	v_exp_f32_e32 v104, v47
	v_exp_f32_e32 v108, v63
	v_exp_f32_e32 v102, v48
	v_exp_f32_e32 v98, v49
	v_exp_f32_e32 v106, v64
	v_exp_f32_e32 v100, v65
	s_waitcnt lgkmcnt(0)
	v_mfma_f32_32x32x16_bf16 v[82:97], v[34:37], v[154:157], v[82:97]
	v_mfma_f32_32x32x16_bf16 v[82:97], v[38:41], v[158:161], v[82:97]
	v_cvt_pk_bf16_f32 v213, v126, v116
	v_cvt_pk_bf16_f32 v214, v186, v168
	v_cvt_pk_bf16_f32 v215, v164, v142
	v_cvt_pk_bf16_f32 v174, v136, v128
	v_cvt_pk_bf16_f32 v175, v120, v114
	v_cvt_pk_bf16_f32 v176, v110, v104
	v_cvt_pk_bf16_f32 v177, v102, v98
	v_cvt_pk_bf16_f32 v178, v162, v138
	v_cvt_pk_bf16_f32 v179, v130, v172
	v_cvt_pk_bf16_f32 v180, v244, v170
	v_cvt_pk_bf16_f32 v181, v166, v144
	v_cvt_pk_bf16_f32 v208, v140, v132
	v_cvt_pk_bf16_f32 v209, v124, v118
	v_cvt_pk_bf16_f32 v210, v112, v108
	v_cvt_pk_bf16_f32 v211, v106, v100
	v_cvt_pk_bf16_f32 v212, v122, v134
	ds_read_b64_tr_b16 v[50:51], v0 offset:16384
	ds_read_b64_tr_b16 v[52:53], v0 offset:16896
	ds_read_b64_tr_b16 v[216:217], v0 offset:20480
	ds_read_b64_tr_b16 v[218:219], v0 offset:20992
	v_exp_f32_e32 v123, v66
	v_exp_f32_e32 v163, v82
	v_exp_f32_e32 v135, v67
	v_exp_f32_e32 v139, v83
	v_exp_f32_e32 v127, v68
	v_exp_f32_e32 v187, v70
	v_exp_f32_e32 v245, v86
	v_exp_f32_e32 v131, v84
	v_exp_f32_e32 v117, v69
	v_exp_f32_e32 v173, v85
	v_exp_f32_e32 v169, v71
	v_exp_f32_e32 v165, v72
	v_exp_f32_e32 v143, v73
	v_exp_f32_e32 v137, v74
	v_exp_f32_e32 v129, v75
	v_exp_f32_e32 v121, v76
	v_exp_f32_e32 v115, v77
	v_exp_f32_e32 v111, v78
	v_exp_f32_e32 v105, v79
	v_exp_f32_e32 v103, v80
	v_exp_f32_e32 v99, v81
	ds_read_b64_tr_b16 v[220:221], v0 offset:17408
	ds_read_b64_tr_b16 v[222:223], v0 offset:17920
	ds_read_b64_tr_b16 v[224:225], v0 offset:21504
	ds_read_b64_tr_b16 v[226:227], v0 offset:22016
	ds_read_b64_tr_b16 v[228:229], v0 offset:18432
	ds_read_b64_tr_b16 v[230:231], v0 offset:18944
	ds_read_b64_tr_b16 v[232:233], v0 offset:22528
	ds_read_b64_tr_b16 v[234:235], v0 offset:23040
	ds_read_b64_tr_b16 v[236:237], v0 offset:19456
	ds_read_b64_tr_b16 v[238:239], v0 offset:19968
	ds_read_b64_tr_b16 v[240:241], v0 offset:23552
	ds_read_b64_tr_b16 v[242:243], v0 offset:24064
	s_waitcnt lgkmcnt(14)
	v_mfma_f32_32x32x16_bf16 v[34:49], v[212:215], v[50:53], v[18:33]
	v_add_f32_e64 v66, v186, v244
	v_add_f32_e64 v67, v187, v245
	v_cvt_pk_bf16_f32 v68, v123, v135
	v_cvt_pk_bf16_f32 v69, v127, v117
	v_cvt_pk_bf16_f32 v70, v187, v169
	v_cvt_pk_bf16_f32 v71, v165, v143
	v_cvt_pk_bf16_f32 v72, v137, v129
	v_cvt_pk_bf16_f32 v73, v121, v115
	v_cvt_pk_bf16_f32 v74, v111, v105
	v_cvt_pk_bf16_f32 v75, v103, v99
	v_cvt_pk_bf16_f32 v76, v163, v139
	v_cvt_pk_bf16_f32 v77, v131, v173
	s_waitcnt lgkmcnt(12)
	v_mfma_f32_32x32x16_bf16 v[50:65], v[212:215], v[216:219], v[2:17]
	v_exp_f32_e32 v171, v87
	v_exp_f32_e32 v167, v88
	v_exp_f32_e32 v145, v89
	v_exp_f32_e32 v141, v90
	v_exp_f32_e32 v133, v91
	v_exp_f32_e32 v125, v92
	v_exp_f32_e32 v119, v93
	v_exp_f32_e32 v113, v94
	v_exp_f32_e32 v109, v95
	v_exp_f32_e32 v107, v96
	v_exp_f32_e32 v101, v97
	v_cvt_pk_bf16_f32 v78, v245, v171
	v_cvt_pk_bf16_f32 v79, v167, v145
	v_cvt_pk_bf16_f32 v80, v141, v133
	v_cvt_pk_bf16_f32 v81, v125, v119
	v_cvt_pk_bf16_f32 v82, v113, v109
	v_cvt_pk_bf16_f32 v83, v107, v101
	s_waitcnt lgkmcnt(10)
	v_mfma_f32_32x32x16_bf16 v[34:49], v[174:177], v[220:223], v[34:49]
	v_add_f32_e64 v84, v122, v162
	v_add_f32_e64 v85, v123, v163
	v_add_f32_e64 v86, v134, v138
	v_add_f32_e64 v87, v135, v139
	v_add_f32_e64 v84, v84, 0
	v_add_f32_e64 v85, v85, 0
	v_pk_add_f32 v[88:89], v[126:127], v[130:131]
	v_pk_add_f32 v[84:85], v[86:87], v[84:85]
	v_pk_add_f32 v[90:91], v[116:117], v[172:173]
	v_pk_add_f32 v[84:85], v[88:89], v[84:85]
	s_waitcnt lgkmcnt(8)
	v_mfma_f32_32x32x16_bf16 v[50:65], v[174:177], v[224:227], v[50:65]
	v_add_f32_e64 v84, v90, v84
	v_add_f32_e64 v85, v91, v85
	v_add_f32_e64 v86, v168, v170
	v_add_f32_e64 v87, v169, v171
	v_add_f32_e64 v66, v66, v84
	v_add_f32_e64 v67, v67, v85
	v_pk_add_f32 v[88:89], v[164:165], v[166:167]
	v_pk_add_f32 v[66:67], v[86:87], v[66:67]
	v_pk_add_f32 v[90:91], v[142:143], v[144:145]
	v_pk_add_f32 v[66:67], v[88:89], v[66:67]
	s_waitcnt lgkmcnt(6)
	v_mfma_f32_32x32x16_bf16 v[34:49], v[178:181], v[228:231], v[34:49]
	v_add_f32_e64 v92, v136, v140
	v_add_f32_e64 v93, v137, v141
	v_add_f32_e64 v66, v90, v66
	v_add_f32_e64 v67, v91, v67
	v_add_f32_e64 v94, v128, v132
	v_add_f32_e64 v95, v129, v133
	v_pk_add_f32 v[66:67], v[92:93], v[66:67]
	v_pk_add_f32 v[96:97], v[120:121], v[124:125]
	v_pk_add_f32 v[66:67], v[94:95], v[66:67]
	v_pk_add_f32 v[114:115], v[114:115], v[118:119]
	s_waitcnt lgkmcnt(4)
	v_mfma_f32_32x32x16_bf16 v[50:65], v[178:181], v[232:235], v[50:65]
	v_add_f32_e64 v66, v96, v66
	v_add_f32_e64 v67, v97, v67
	v_add_f32_e64 v110, v110, v112
	v_add_f32_e64 v111, v111, v113
	v_add_f32_e64 v66, v114, v66
	v_add_f32_e64 v67, v115, v67
	v_pk_add_f32 v[104:105], v[104:105], v[108:109]
	v_pk_add_f32 v[66:67], v[110:111], v[66:67]
	v_pk_add_f32 v[102:103], v[102:103], v[106:107]
	v_pk_add_f32 v[66:67], v[104:105], v[66:67]
	s_waitcnt lgkmcnt(2)
	v_mfma_f32_32x32x16_bf16 v[34:49], v[208:211], v[236:239], v[34:49]
	v_add_f32_e64 v98, v98, v100
	v_add_f32_e64 v99, v99, v101
	v_add_f32_e64 v66, v102, v66
	v_add_f32_e64 v67, v103, v67
	v_add_f32_e64 v66, v98, v66
	v_add_f32_e64 v67, v99, v67
	v_add_f32_e32 v66, v205, v66
	s_waitcnt lgkmcnt(0)
	v_mfma_f32_32x32x16_bf16 v[50:65], v[208:211], v[240:243], v[50:65]
	v_add_f32_e32 v66, v66, v67
	ds_read_b64_tr_b16 v[84:85], v0 offset:24576
	ds_read_b64_tr_b16 v[86:87], v0 offset:25088
	ds_read_b64_tr_b16 v[88:89], v0 offset:25600
	ds_read_b64_tr_b16 v[90:91], v0 offset:26112
	s_waitcnt lgkmcnt(2)
	v_mfma_f32_32x32x16_bf16 v[34:49], v[68:71], v[84:87], v[34:49]
	ds_read_b64_tr_b16 v[84:85], v0 offset:28672
	ds_read_b64_tr_b16 v[86:87], v0 offset:29184
	ds_read_b64_tr_b16 v[92:93], v0 offset:29696
	ds_read_b64_tr_b16 v[94:95], v0 offset:30208
	s_waitcnt lgkmcnt(2)
	v_mfma_f32_32x32x16_bf16 v[50:65], v[68:71], v[84:87], v[50:65]
	ds_read_b64_tr_b16 v[68:69], v0 offset:26624
	ds_read_b64_tr_b16 v[70:71], v0 offset:27136
	ds_read_b64_tr_b16 v[84:85], v0 offset:31744
	ds_read_b64_tr_b16 v[86:87], v0 offset:32256
	v_mfma_f32_32x32x16_bf16 v[34:49], v[72:75], v[88:91], v[34:49]
	s_waitcnt lgkmcnt(4)
	v_mfma_f32_32x32x16_bf16 v[50:65], v[72:75], v[92:95], v[50:65]
	ds_read_b64_tr_b16 v[72:73], v0 offset:27648
	ds_read_b64_tr_b16 v[74:75], v0 offset:28160
	s_waitcnt lgkmcnt(4)
	v_mfma_f32_32x32x16_bf16 v[34:49], v[76:79], v[68:71], v[34:49]
	ds_read_b64_tr_b16 v[68:69], v0 offset:30720
	ds_read_b64_tr_b16 v[70:71], v0 offset:31232
	s_waitcnt lgkmcnt(0)
	v_mfma_f32_32x32x16_bf16 v[50:65], v[76:79], v[68:71], v[50:65]
	v_mfma_f32_32x32x16_bf16 v[34:49], v[80:83], v[72:75], v[34:49]
	v_mfma_f32_32x32x16_bf16 v[50:65], v[80:83], v[84:87], v[50:65]
